# bundle: norm prefetch + all GEMM LDS-DMA address builds scalar + attention tile loop issues LDS reads before bias loads and DMA
# baseline (speedup 1.0000x reference)
.Lat_wdone:
	s_barrier
	s_cmp_lt_u32 s71, s78
	s_cbranch_scc0 .Lat_ctx_tile
	s_add_i32 s27, s32, s71
	s_sub_i32 s70, s27, s15
	s_cmp_lt_u32 s70, s2
	s_cselect_b32 s100, 1, 0
	s_cbranch_scc0 .Lat_loc_dma
	v_add_u32_e32 v242, s99, v255
	v_xor_b32_e32 v243, 64, v255
	v_xor_b32_e32 v244, 0x80, v255
	v_xor_b32_e32 v245, 0xc0, v255
	v_add_u32_e32 v243, s99, v243
	v_add_u32_e32 v244, s99, v244
	v_add_u32_e32 v245, s99, v245
	v_add_u32_e32 v246, s99, v191
	ds_read_b128 v[142:145], v242
	ds_read_b128 v[130:133], v243
	ds_read_b128 v[134:137], v244
	ds_read_b128 v[138:141], v245
	ds_read_b128 v[158:161], v242 offset:1024
	ds_read_b128 v[150:153], v243 offset:1024
	ds_read_b128 v[154:157], v244 offset:1024
	ds_read_b128 v[146:149], v245 offset:1024
	ds_read_b128 v[126:129], v246
	ds_read_b128 v[122:125], v246 offset:2048
	ds_read_b128 v[118:121], v246 offset:4096
	ds_read_b128 v[114:117], v246 offset:6144
	ds_read_b128 v[110:113], v246 offset:8192
	ds_read_b128 v[106:109], v246 offset:10240
	ds_read_b128 v[102:105], v246 offset:12288
	ds_read_b128 v[98:101], v246 offset:14336
	v_add_u32_e32 v247, 8, v188
	v_med3_i32 v247, v247, 0, s22
	v_lshlrev_b32_e32 v247, 2, v247
	global_load_dword v213, v247, s[0:1]
	v_add_u32_e32 v248, 9, v188
	v_med3_i32 v248, v248, 0, s22
	v_lshlrev_b32_e32 v248, 2, v248
	global_load_dword v214, v248, s[0:1]
	v_add_u32_e32 v247, 10, v188
	v_med3_i32 v247, v247, 0, s22
	v_lshlrev_b32_e32 v247, 2, v247
	global_load_dword v215, v247, s[0:1]
	v_add_u32_e32 v248, 11, v188
	v_med3_i32 v248, v248, 0, s22
	v_lshlrev_b32_e32 v248, 2, v248
	global_load_dword v216, v248, s[0:1]
	v_add_u32_e32 v247, 12, v188
	v_med3_i32 v247, v247, 0, s22
	v_lshlrev_b32_e32 v247, 2, v247
	global_load_dword v217, v247, s[0:1]
	v_add_u32_e32 v248, 13, v188
	v_med3_i32 v248, v248, 0, s22
	v_lshlrev_b32_e32 v248, 2, v248
	global_load_dword v218, v248, s[0:1]
	v_add_u32_e32 v247, 14, v188
	v_med3_i32 v247, v247, 0, s22
	v_lshlrev_b32_e32 v247, 2, v247
	global_load_dword v219, v247, s[0:1]
	v_add_u32_e32 v248, 15, v188
	v_med3_i32 v248, v248, 0, s22
	v_lshlrev_b32_e32 v248, 2, v248
	global_load_dword v220, v248, s[0:1]
	v_subrev_u32_e32 v247, 23, v188
	v_med3_i32 v247, v247, 0, s22
	v_lshlrev_b32_e32 v247, 2, v247
	global_load_dword v221, v247, s[0:1]
	v_subrev_u32_e32 v248, 22, v188
	v_med3_i32 v248, v248, 0, s22
	v_lshlrev_b32_e32 v248, 2, v248
	global_load_dword v222, v248, s[0:1]
	v_subrev_u32_e32 v247, 21, v188
	v_med3_i32 v247, v247, 0, s22
	v_lshlrev_b32_e32 v247, 2, v247
	global_load_dword v223, v247, s[0:1]
	v_subrev_u32_e32 v248, 20, v188
	v_med3_i32 v248, v248, 0, s22
	v_lshlrev_b32_e32 v248, 2, v248
	global_load_dword v224, v248, s[0:1]
	v_subrev_u32_e32 v247, 19, v188
	v_med3_i32 v247, v247, 0, s22
	v_lshlrev_b32_e32 v247, 2, v247
	global_load_dword v225, v247, s[0:1]
	v_subrev_u32_e32 v248, 18, v188
	v_med3_i32 v248, v248, 0, s22
	v_lshlrev_b32_e32 v248, 2, v248
	global_load_dword v226, v248, s[0:1]
	v_subrev_u32_e32 v247, 17, v188
	v_med3_i32 v247, v247, 0, s22
	v_lshlrev_b32_e32 v247, 2, v247
	global_load_dword v227, v247, s[0:1]
	v_subrev_u32_e32 v248, 16, v188
	v_med3_i32 v248, v248, 0, s22
	v_lshlrev_b32_e32 v248, 2, v248
	global_load_dword v228, v248, s[0:1]
	s_add_i32 s9, s71, 2
	s_sub_i32 s27, s9, s78
	s_lshr_b32 s42, s23, 9
	s_lshl_b32 s101, s42, 2
	s_add_i32 s27, s27, s101
	s_add_i32 s27, s27, 0x100
	s_lshl_b32 s42, s42, 5
	s_add_i32 s42, s42, s32
	s_add_i32 s42, s42, s9
	s_cmp_lt_u32 s9, s78
	s_cselect_b32 s27, s42, s27
	s_lshl_b32 s27, s27, 6
	s_mul_i32 s42, s27, s37
	s_add_u32 s10, s50, s42
	s_addc_u32 s11, s51, 0
	s_lshl_b32 s101, s13, 1
	s_add_i32 s101, s101, 0x2800
	s_add_u32 s10, s10, s101
	s_addc_u32 s11, s11, 0
	s_lshl_b32 s8, s12, 10
	s_add_i32 s8, s8, s98
	s_mov_b32 m0, s8
	s_add_i32 s8, s8, 0x2000
	global_load_lds_dwordx4 v229, s[10:11]
	s_mov_b32 m0, s8
	s_add_u32 s10, s10, 0xd0000
	s_addc_u32 s11, s11, 0
	global_load_lds_dwordx4 v229, s[10:11]
	v_readlane_b32 s10, v252, 55
	v_readlane_b32 s11, v252, 56
	s_mul_i32 s42, s13, 0x9000
	s_lshl_b32 s101, s27, 1
	s_add_i32 s42, s42, s101
	s_add_i32 s8, s8, 0x2000
	s_add_u32 s10, s10, s42
	s_addc_u32 s11, s11, 0
	s_mov_b32 m0, s8
	s_add_i32 s8, s8, 0x2000
	global_load_lds_dwordx4 v254, s[10:11]
	s_mov_b32 m0, s8
	s_add_u32 s10, s10, 0x240000
	s_addc_u32 s11, s11, 0
	global_load_lds_dwordx4 v254, s[10:11]
	s_add_i32 s98, s98, 0x8000
	s_cmp_eq_u32 s98, 0x18000
	s_cselect_b32 s98, 0x0, s98
	s_mov_b32 s100, 2
	s_branch .Lat_body

.Lat_ctx_tile:
	v_add_u32_e32 v242, s99, v190
	v_xor_b32_e32 v243, 64, v190
	v_xor_b32_e32 v244, 0x80, v190
	v_xor_b32_e32 v245, 0xc0, v190
	v_add_u32_e32 v243, s99, v243
	v_add_u32_e32 v244, s99, v244
	v_add_u32_e32 v245, s99, v245
	v_add_u32_e32 v246, s99, v181
	ds_read_b128 v[142:145], v242
	ds_read_b128 v[130:133], v243
	ds_read_b128 v[134:137], v244
	ds_read_b128 v[138:141], v245
	ds_read_b128 v[158:161], v242 offset:1024
	ds_read_b128 v[150:153], v243 offset:1024
	ds_read_b128 v[154:157], v244 offset:1024
	ds_read_b128 v[146:149], v245 offset:1024
	ds_read_b128 v[126:129], v246
	ds_read_b128 v[122:125], v246 offset:2048
	ds_read_b128 v[118:121], v246 offset:4096
	ds_read_b128 v[114:117], v246 offset:6144
	ds_read_b128 v[110:113], v246 offset:8192
	ds_read_b128 v[106:109], v246 offset:10240
	ds_read_b128 v[102:105], v246 offset:12288
	ds_read_b128 v[98:101], v246 offset:14336
	s_add_i32 s9, s71, 2
	s_add_i32 s42, s78, 4
	s_cmp_lt_u32 s9, s42
	s_cbranch_scc0 .Lat_ctx_nodma
	s_sub_i32 s27, s9, s78
	s_lshr_b32 s42, s23, 9
	s_lshl_b32 s101, s42, 2
	s_add_i32 s27, s27, s101
	s_add_i32 s27, s27, 0x100
	s_lshl_b32 s42, s42, 5
	s_add_i32 s42, s42, s32
	s_add_i32 s42, s42, s9
	s_cmp_lt_u32 s9, s78
	s_cselect_b32 s27, s42, s27
	s_lshl_b32 s27, s27, 6
	s_mul_i32 s42, s27, s37
	s_add_u32 s10, s50, s42
	s_addc_u32 s11, s51, 0
	s_lshl_b32 s101, s13, 1
	s_add_i32 s101, s101, 0x2800
	s_add_u32 s10, s10, s101
	s_addc_u32 s11, s11, 0
	s_lshl_b32 s8, s12, 10
	s_add_i32 s8, s8, s98
	s_mov_b32 m0, s8
	s_add_i32 s8, s8, 0x2000
	global_load_lds_dwordx4 v229, s[10:11]
	s_mov_b32 m0, s8
	s_add_u32 s10, s10, 0xd0000
	s_addc_u32 s11, s11, 0
	global_load_lds_dwordx4 v229, s[10:11]
	v_readlane_b32 s10, v252, 55
	v_readlane_b32 s11, v252, 56
	s_mul_i32 s42, s13, 0x9000
	s_lshl_b32 s101, s27, 1
	s_add_i32 s42, s42, s101
	s_add_i32 s8, s8, 0x2000
	s_add_u32 s10, s10, s42
	s_addc_u32 s11, s11, 0
	s_mov_b32 m0, s8
	s_add_i32 s8, s8, 0x2000
	global_load_lds_dwordx4 v254, s[10:11]
	s_mov_b32 m0, s8
	s_add_u32 s10, s10, 0x240000
	s_addc_u32 s11, s11, 0
	global_load_lds_dwordx4 v254, s[10:11]
	s_add_i32 s98, s98, 0x8000
	s_cmp_eq_u32 s98, 0x18000
	s_cselect_b32 s98, 0x0, s98
.Lat_ctx_nodma:
	s_sub_i32 s27, s71, s78
	s_lshl_b32 s27, s27, 1
	s_add_i32 s70, s2, s27
	s_mov_b32 s100, 0
	s_branch .Lat_body
